# v23 + lever 2 prologue de-serialisation: K-tile 1 staging loads issued before the first prologue wait (vmcnt(2)->vmcnt(8)) in all five GEMM phases
# speedup vs baseline: 1.0307x; 1.0307x over previous
.LBB0_218:
	s_add_u32 s89, s54, 0x2c00000
	s_addc_u32 s90, s55, 0
	s_add_u32 s4, s54, 0x4c00000
	v_writelane_b32 v251, s4, 29
	s_addc_u32 s4, s55, 0
	s_add_u32 s93, s54, 0x6c00000
	s_addc_u32 s94, s55, 0
	s_add_u32 s68, s54, 0x480000
	v_writelane_b32 v251, s4, 30
	s_addc_u32 s4, s55, 0
	s_add_u32 s14, s54, 0x4c0000
	s_addc_u32 s15, s55, 0
	s_bfe_u32 s95, s96, 0x20006
	v_writelane_b32 v251, s14, 31
	s_mov_b32 s5, s96
	s_lshl_b32 s96, s12, 6
	s_lshl_b32 s10, s95, 5
	v_writelane_b32 v251, s15, 32
	s_cmpk_lt_u32 s5, 0x100
	v_writelane_b32 v251, s10, 33
	s_cselect_b64 s[82:83], -1, 0
	s_cmpk_gt_u32 s5, 0xff
	v_writelane_b32 v251, s5, 34
	s_cselect_b64 s[14:15], -1, 0
	v_writelane_b32 v251, s14, 35
	s_lshl_b32 s97, s95, 7
	s_add_i32 s10, 0, 0x22400
	v_writelane_b32 v251, s15, 36
	s_mov_b32 s63, s61
	s_lshl_b32 s5, s62, 7
	s_add_i32 s11, s10, s97
	s_lshl_b64 s[42:43], s[62:63], 13
	v_writelane_b32 v251, s11, 37
	s_mov_b32 s63, s10
	s_add_i32 s10, s10, s5
	v_writelane_b32 v251, s10, 38
	v_writelane_b32 v251, s5, 39
	s_add_i32 s5, s5, 0
	s_add_i32 s5, s5, 0x22600
	v_writelane_b32 v251, s5, 40
	s_lshl_b32 s65, s95, 4
	s_ashr_i32 s64, s58, 31
	v_readlane_b32 s16, v251, 2
	v_readlane_b32 s17, v251, 3
	s_add_u32 s44, s16, 0x1000
	s_addc_u32 s45, s17, 0
	s_add_u32 s46, s16, 0x2000
	s_mov_b64 s[48:49], 0x80
	s_addc_u32 s47, s17, 0
	v_lshl_add_u64 v[2:3], v[2:3], 0, s[48:49]
	s_add_i32 m0, s79, 0x18000
	s_and_b32 s69, s4, 0xffff
	global_load_lds_dwordx4 v[2:3], off
	s_add_i32 m0, s79, 0x1a000
	s_add_u32 s4, s6, 0x8000
	v_lshl_add_u64 v[0:1], v[0:1], 0, s[48:49]
	s_addc_u32 s5, s7, 0
	s_add_i32 s33, s79, 0x8000
	global_load_lds_dwordx4 v[0:1], off
	v_lshl_add_u64 v[0:1], s[4:5], 0, v[144:145]
	s_mov_b32 m0, s33
	s_add_i32 s56, s79, 0xa000
	global_load_lds_dwordx4 v[0:1], off
	v_lshl_add_u64 v[0:1], s[4:5], 0, v[148:149]
	s_add_u32 s4, s8, 0x40080
	s_mov_b32 m0, s56
	s_addc_u32 s5, s9, 0
	global_load_lds_dwordx4 v[0:1], off
	v_lshl_add_u64 v[0:1], s[4:5], 0, v[146:147]
	s_add_i32 m0, s79, 0x1c000
	v_and_b32_e32 v176, 15, v4
	global_load_lds_dwordx4 v[0:1], off
	v_lshl_add_u64 v[0:1], s[4:5], 0, v[150:151]
	s_add_i32 m0, s79, 0x1e000
	v_lshlrev_b32_e32 v3, 2, v4
	global_load_lds_dwordx4 v[0:1], off
	s_waitcnt vmcnt(8)
	s_barrier
	v_and_b32_e32 v0, 48, v4
	v_and_b32_e32 v1, 0xfffffc00, v6
	v_lshl_add_u32 v2, s12, 13, v1
	v_lshl_or_b32 v0, v176, 6, v0
	v_and_b32_e32 v3, 32, v3
	v_lshl_add_u32 v1, s95, 12, v1
	v_bitop3_b32 v2, v0, v2, v3 bitop3:0xde
	v_bitop3_b32 v178, v0, v1, v3 bitop3:0xde
	v_lshlrev_b32_e32 v0, 9, v5
	v_and_b32_e32 v0, 0x7ffffc00, v0
	v_add3_u32 v0, v0, v7, v8
	v_add_lshl_u32 v152, v0, v9, 1
	v_lshlrev_b32_e32 v0, 9, v10
	v_and_b32_e32 v0, 0x7ffffc00, v0
	v_readlane_b32 s28, v251, 14
	v_readlane_b32 s29, v251, 15
	v_readlane_b32 s30, v251, 16
	v_readlane_b32 s31, v251, 17
	s_waitcnt vmcnt(6)
	s_mov_b64 s[4:5], 0xc000
	v_add3_u32 v0, v0, v11, v12
	s_mov_b32 s71, 0x20000
	s_mov_b32 s70, 0x40000
	s_mov_b64 s[28:29], s[68:69]
	v_lshl_add_u64 v[154:155], v[152:153], 0, s[4:5]
	v_add_lshl_u32 v152, v0, v13, 1
	s_add_i32 s34, 0, 0x10000
	s_add_i32 s35, 0, 0x14000
	s_mov_b64 s[30:31], s[70:71]
	v_ashrrev_i32_e32 v177, 4, v4
	v_lshl_add_u64 v[156:157], v[152:153], 0, s[4:5]
	v_mov_b64_e32 v[158:159], 0x800
	v_mov_b64_e32 v[160:161], 0x7ff
	v_add_u32_e32 v179, s34, v178
	v_add_u32_e32 v180, s35, v178
	v_add_u32_e32 v181, 0, v2
	s_mov_b32 s57, 0xc2fc0000
	v_mov_b32_e32 v182, 0x42800000
	v_not_b32_e32 v183, 63
	v_mov_b32_e32 v184, 0x3db504f3
	s_mov_b32 s91, 0
	s_mov_b32 s66, 0x437f0000
	v_readlane_b32 s18, v251, 4
	v_readlane_b32 s19, v251, 5
	v_readlane_b32 s20, v251, 6
	v_readlane_b32 s21, v251, 7
	v_readlane_b32 s22, v251, 8
	v_readlane_b32 s23, v251, 9
	v_readlane_b32 s24, v251, 10
	v_readlane_b32 s25, v251, 11
	v_readlane_b32 s26, v251, 12
	v_readlane_b32 s27, v251, 13
	s_barrier
	s_branch .LBB0_221

.LBB0_439:
	s_add_u32 s69, s54, 0x2c00000
	s_mov_b64 s[10:11], 0x80
	s_addc_u32 s70, s55, 0
	v_lshl_add_u64 v[4:5], v[4:5], 0, s[10:11]
	s_add_i32 m0, s35, 0x18000
	s_bfe_u32 s71, s96, 0x20006
	s_lshl_b32 s72, s5, 6
	s_lshl_b64 s[8:9], s[62:63], 13
	s_ashr_i32 s73, s58, 31
	global_load_lds_dwordx4 v[4:5], off
	s_add_i32 m0, s35, 0x1a000
	s_add_u32 s12, s38, 0x8000
	v_lshl_add_u64 v[2:3], v[2:3], 0, s[10:11]
	s_addc_u32 s13, s39, 0
	s_add_i32 s74, s35, 0x8000
	global_load_lds_dwordx4 v[2:3], off
	v_lshl_add_u64 v[2:3], s[12:13], 0, v[194:195]
	s_mov_b32 m0, s74
	s_add_i32 s75, s35, 0xa000
	global_load_lds_dwordx4 v[2:3], off
	v_lshl_add_u64 v[2:3], s[12:13], 0, v[190:191]
	s_add_u32 s12, s46, 0x80080
	s_mov_b32 m0, s75
	s_addc_u32 s13, s47, 0
	global_load_lds_dwordx4 v[2:3], off
	v_lshl_add_u64 v[2:3], s[12:13], 0, v[192:193]
	s_add_i32 m0, s35, 0x1c000
	v_and_b32_e32 v208, 15, v1
	global_load_lds_dwordx4 v[2:3], off
	v_lshl_add_u64 v[2:3], s[12:13], 0, v[188:189]
	s_add_i32 m0, s35, 0x1e000
	v_ashrrev_i32_e32 v209, 4, v1
	global_load_lds_dwordx4 v[2:3], off
	s_waitcnt vmcnt(8)
	s_barrier
	v_and_b32_e32 v2, 48, v1
	v_and_b32_e32 v3, 0xfffffc00, v8
	v_lshlrev_b32_e32 v1, 2, v1
	v_lshl_add_u32 v4, s5, 13, v3
	v_lshl_or_b32 v2, v208, 6, v2
	v_and_b32_e32 v1, 32, v1
	v_lshl_add_u32 v3, s71, 12, v3
	v_bitop3_b32 v4, v2, v4, v1 bitop3:0xde
	v_bitop3_b32 v210, v2, v3, v1 bitop3:0xde
	v_lshlrev_b32_e32 v1, 8, v11
	v_and_b32_e32 v1, 0x7ffffe00, v1
	v_lshlrev_b32_e32 v2, 5, v12
	v_add3_u32 v1, v13, v1, v2
	s_sext_i32_i8 s40, s4
	v_add_lshl_u32 v2, v1, v14, 1
	v_mov_b32_e32 v3, v0
	s_mov_b64 s[4:5], 0xa000
	v_lshlrev_b32_e32 v1, 8, v6
	v_lshl_add_u64 v[196:197], v[2:3], 0, s[4:5]
	v_and_b32_e32 v1, 0x7ffffe00, v1
	v_lshlrev_b32_e32 v2, 5, v7
	s_waitcnt vmcnt(6)
	v_add3_u32 v1, v9, v1, v2
	v_add_lshl_u32 v2, v1, v10, 1
	v_lshl_add_u64 v[198:199], v[2:3], 0, s[4:5]
	v_mov_b64_e32 v[200:201], 0x100
	v_mov_b64_e32 v[202:203], 0xff
	s_movk_i32 s76, 0x1000
	s_mov_b32 s77, 0x41000
	s_add_i32 s78, 0, 0x10000
	s_add_i32 s79, 0, 0x14000
	v_add_u32_e32 v211, 0, v4
	s_mov_b64 s[12:13], 0x140000
	s_mov_b32 s80, 0x141000
	s_mov_b32 s16, 0x3b808081
	s_barrier
	s_branch .LBB0_441

.LBB0_498:
	s_add_u32 s67, s54, 0x4c00000
	s_addc_u32 s68, s55, 0
	s_add_u32 s69, s54, 0x280000
	s_addc_u32 s70, s55, 0
	s_add_u32 s12, s54, 0x300000
	s_mov_b64 s[16:17], 0x80
	s_addc_u32 s13, s55, 0
	s_bfe_u32 s71, s96, 0x20006
	v_lshl_add_u64 v[2:3], v[2:3], 0, s[16:17]
	s_add_i32 m0, s23, 0x18000
	s_lshl_b32 s72, s18, 6
	s_lshl_b32 s73, s71, 5
	s_ashr_i32 s74, s58, 31
	global_load_lds_dwordx4 v[2:3], off
	s_add_i32 m0, s23, 0x1a000
	s_add_u32 s4, s42, 0x8000
	v_lshl_add_u64 v[0:1], v[0:1], 0, s[16:17]
	s_addc_u32 s5, s43, 0
	s_add_i32 s75, s23, 0x8000
	global_load_lds_dwordx4 v[0:1], off
	v_lshl_add_u64 v[0:1], s[4:5], 0, v[192:193]
	s_mov_b32 m0, s75
	s_add_i32 s76, s23, 0xa000
	global_load_lds_dwordx4 v[0:1], off
	v_lshl_add_u64 v[0:1], s[4:5], 0, v[196:197]
	s_add_u32 s4, s44, 0x40080
	s_mov_b32 m0, s76
	s_addc_u32 s5, s45, 0
	global_load_lds_dwordx4 v[0:1], off
	v_lshl_add_u64 v[0:1], s[4:5], 0, v[194:195]
	s_add_i32 m0, s23, 0x1c000
	v_and_b32_e32 v226, 15, v4
	global_load_lds_dwordx4 v[0:1], off
	v_lshl_add_u64 v[0:1], s[4:5], 0, v[198:199]
	s_add_i32 m0, s23, 0x1e000
	v_lshlrev_b32_e32 v3, 2, v4
	global_load_lds_dwordx4 v[0:1], off
	s_waitcnt vmcnt(8)
	s_barrier
	v_and_b32_e32 v0, 48, v4
	v_and_b32_e32 v1, 0xfffffc00, v6
	v_lshl_add_u32 v2, s18, 13, v1
	v_lshl_or_b32 v0, v226, 6, v0
	v_and_b32_e32 v3, 32, v3
	v_lshl_add_u32 v1, s71, 12, v1
	v_bitop3_b32 v2, v0, v2, v3 bitop3:0xde
	v_bitop3_b32 v228, v0, v1, v3 bitop3:0xde
	v_lshlrev_b32_e32 v0, 8, v5
	v_and_b32_e32 v0, 0x7ffffe00, v0
	v_lshlrev_b32_e32 v1, 5, v7
	v_add3_u32 v0, v8, v0, v1
	v_add_lshl_u32 v0, v0, v9, 1
	v_mov_b32_e32 v1, v195
	s_mov_b64 s[4:5], 0xa000
	v_lshl_add_u64 v[200:201], v[0:1], 0, s[4:5]
	v_lshlrev_b32_e32 v0, 8, v10
	v_and_b32_e32 v0, 0x7ffffe00, v0
	v_lshlrev_b32_e32 v1, 5, v11
	v_add3_u32 v0, v12, v0, v1
	s_waitcnt vmcnt(6)
	v_add_lshl_u32 v0, v0, v13, 1
	v_mov_b32_e32 v1, v195
	v_lshl_add_u64 v[202:203], v[0:1], 0, s[4:5]
	s_add_i32 s77, 0, 0x10000
	s_add_i32 s78, 0, 0x14000
	v_mbcnt_lo_u32_b32 v0, -1, 0
	v_ashrrev_i32_e32 v227, 4, v4
	v_mov_b64_e32 v[204:205], 0x100
	v_mov_b64_e32 v[206:207], 0xff
	v_add_u32_e32 v229, s77, v228
	v_add_u32_e32 v230, s78, v228
	v_add_u32_e32 v231, 0, v2
	v_mbcnt_hi_u32_b32 v232, -1, v0
	s_mov_b64 s[18:19], 0x4000
	s_mov_b32 s79, 0
	s_barrier
	s_branch .LBB0_500

.LBB0_558:
	s_bfe_u32 s56, s96, 0x20006
	s_lshl_b32 s57, s5, 6
	s_add_u32 s59, s54, 0x2a0000
	s_addc_u32 s61, s55, 0
	s_add_u32 s64, s54, 0x6c00000
	s_addc_u32 s65, s55, 0
	s_lshl_b32 s66, s56, 5
	s_cmpk_lt_u32 s96, 0x100
	s_mov_b64 s[12:13], 0x80
	s_cselect_b64 s[10:11], -1, 0
	v_lshl_add_u64 v[2:3], v[2:3], 0, s[12:13]
	s_add_i32 m0, s44, 0x18000
	s_ashr_i32 s67, s58, 31
	global_load_lds_dwordx4 v[2:3], off
	s_add_i32 m0, s44, 0x1a000
	s_add_u32 s16, s28, 0x8000
	v_lshl_add_u64 v[0:1], v[0:1], 0, s[12:13]
	s_addc_u32 s17, s29, 0
	s_add_i32 s68, s44, 0x8000
	global_load_lds_dwordx4 v[0:1], off
	v_lshl_add_u64 v[0:1], s[16:17], 0, v[150:151]
	s_mov_b32 m0, s68
	s_add_i32 s69, s44, 0xa000
	global_load_lds_dwordx4 v[0:1], off
	v_lshl_add_u64 v[0:1], s[16:17], 0, v[146:147]
	s_add_u32 s16, s36, 0x40080
	s_mov_b32 m0, s69
	s_addc_u32 s17, s37, 0
	global_load_lds_dwordx4 v[0:1], off
	v_lshl_add_u64 v[0:1], s[16:17], 0, v[148:149]
	s_add_i32 m0, s44, 0x1c000
	v_and_b32_e32 v164, 15, v4
	global_load_lds_dwordx4 v[0:1], off
	v_lshl_add_u64 v[0:1], s[16:17], 0, v[144:145]
	s_add_i32 m0, s44, 0x1e000
	v_lshlrev_b32_e32 v3, 2, v4
	global_load_lds_dwordx4 v[0:1], off
	s_waitcnt vmcnt(8)
	s_barrier
	v_and_b32_e32 v0, 48, v4
	v_and_b32_e32 v1, 0xfffffc00, v5
	v_lshl_add_u32 v2, s5, 13, v1
	v_lshl_or_b32 v0, v164, 6, v0
	v_and_b32_e32 v3, 32, v3
	v_lshl_add_u32 v1, s56, 12, v1
	v_bitop3_b32 v2, v0, v2, v3 bitop3:0xde
	v_bitop3_b32 v166, v0, v1, v3 bitop3:0xde
	v_lshlrev_b32_e32 v0, 8, v10
	v_and_b32_e32 v0, 0x7ffffe00, v0
	v_lshlrev_b32_e32 v1, 5, v11
	v_add3_u32 v0, v12, v0, v1
	s_sext_i32_i8 s72, s4
	v_add_lshl_u32 v0, v0, v13, 1
	v_mov_b32_e32 v1, v149
	s_mov_b64 s[4:5], 0xa000
	v_lshl_add_u64 v[152:153], v[0:1], 0, s[4:5]
	v_lshlrev_b32_e32 v0, 8, v6
	v_and_b32_e32 v0, 0x7ffffe00, v0
	v_lshlrev_b32_e32 v1, 5, v7
	s_waitcnt vmcnt(6)
	v_add3_u32 v0, v8, v0, v1
	v_add_lshl_u32 v0, v0, v9, 1
	v_mov_b32_e32 v1, v149
	s_add_i32 s70, 0, 0x10000
	s_add_i32 s71, 0, 0x14000
	v_ashrrev_i32_e32 v165, 4, v4
	v_lshl_add_u64 v[154:155], v[0:1], 0, s[4:5]
	v_mov_b64_e32 v[156:157], 0x400
	v_mov_b64_e32 v[158:159], 0x3ff
	v_add_u32_e32 v167, s70, v166
	v_add_u32_e32 v168, s71, v166
	v_add_u32_e32 v169, 0, v2
	s_barrier
	s_branch .LBB0_561

.LBB0_606:
	s_mov_b64 s[16:17], 0x80
	s_add_i32 m0, s44, 0x18000
	v_lshl_add_u64 v[2:3], v[2:3], 0, s[16:17]
	s_bfe_u32 s9, s96, 0x20006
	s_lshl_b32 s7, s1, 6
	global_load_lds_dwordx4 v[2:3], off
	s_add_i32 m0, s44, 0x1a000
	s_add_u32 s4, s12, 0x8000
	v_lshl_add_u64 v[0:1], v[0:1], 0, s[16:17]
	s_addc_u32 s5, s13, 0
	s_add_i32 s48, s44, 0x8000
	global_load_lds_dwordx4 v[0:1], off
	v_lshl_add_u64 v[0:1], s[4:5], 0, v[128:129]
	s_mov_b32 m0, s48
	s_add_i32 s49, s44, 0xa000
	global_load_lds_dwordx4 v[0:1], off
	v_lshl_add_u64 v[0:1], s[4:5], 0, v[132:133]
	s_add_u32 s4, s10, 0x100080
	s_mov_b32 m0, s49
	s_addc_u32 s5, s11, 0
	global_load_lds_dwordx4 v[0:1], off
	s_add_i32 m0, s44, 0x1c000
	v_lshl_add_u64 v[0:1], s[4:5], 0, v[130:131]
	global_load_lds_dwordx4 v[0:1], off
	v_lshl_add_u64 v[0:1], s[4:5], 0, v[134:135]
	s_add_i32 m0, s44, 0x1e000
	v_and_b32_e32 v148, 15, v228
	global_load_lds_dwordx4 v[0:1], off
	s_waitcnt vmcnt(8)
	s_barrier
	v_and_b32_e32 v0, 48, v228
	v_and_b32_e32 v1, 0xfffffc00, v5
	v_lshlrev_b32_e32 v3, 2, v228
	v_lshl_add_u32 v2, s1, 13, v1
	v_lshl_or_b32 v0, v148, 6, v0
	v_and_b32_e32 v3, 32, v3
	v_lshl_add_u32 v1, s9, 12, v1
	v_bitop3_b32 v5, v0, v2, v3 bitop3:0xde
	v_bitop3_b32 v149, v0, v1, v3 bitop3:0xde
	v_lshlrev_b32_e32 v0, 8, v4
	v_and_b32_e32 v0, 0x7ffffe00, v0
	v_lshlrev_b32_e32 v1, 5, v6
	v_add3_u32 v0, v7, v0, v1
	s_sext_i32_i8 s8, s0
	v_add_lshl_u32 v0, v0, v8, 1
	v_mov_b32_e32 v1, v131
	s_mov_b64 s[0:1], 0xa000
	v_lshl_add_u64 v[136:137], v[0:1], 0, s[0:1]
	v_lshlrev_b32_e32 v0, 8, v9
	v_and_b32_e32 v0, 0x7ffffe00, v0
	v_lshlrev_b32_e32 v1, 5, v10
	v_add3_u32 v0, v11, v0, v1
	s_waitcnt vmcnt(6)
	v_add_lshl_u32 v0, v0, v12, 1
	v_mov_b32_e32 v1, v131
	v_mov_b32_e32 v2, v131
	v_mov_b32_e32 v3, v131
	v_lshl_add_u64 v[138:139], v[0:1], 0, s[0:1]
	v_mov_b32_e32 v0, v131
	v_add_u32_e32 v150, 0, v5
	v_mov_b64_e32 v[6:7], v[2:3]
	v_mov_b64_e32 v[18:19], v[2:3]
	v_mov_b64_e32 v[22:23], v[2:3]
	v_mov_b64_e32 v[34:35], v[2:3]
	v_mov_b64_e32 v[38:39], v[2:3]
	v_mov_b64_e32 v[50:51], v[2:3]
	v_mov_b64_e32 v[54:55], v[2:3]
	v_mov_b64_e32 v[10:11], v[2:3]
	v_mov_b64_e32 v[14:15], v[2:3]
	v_mov_b64_e32 v[26:27], v[2:3]
	v_mov_b64_e32 v[30:31], v[2:3]
	v_mov_b64_e32 v[42:43], v[2:3]
	v_mov_b64_e32 v[46:47], v[2:3]
	v_mov_b64_e32 v[58:59], v[2:3]
	v_mov_b64_e32 v[62:63], v[2:3]
	v_mov_b64_e32 v[66:67], v[2:3]
	v_mov_b64_e32 v[70:71], v[2:3]
	v_mov_b64_e32 v[82:83], v[2:3]
	v_mov_b64_e32 v[86:87], v[2:3]
	v_mov_b64_e32 v[98:99], v[2:3]
	v_mov_b64_e32 v[102:103], v[2:3]
	v_mov_b64_e32 v[114:115], v[2:3]
	v_mov_b64_e32 v[118:119], v[2:3]
	v_mov_b64_e32 v[74:75], v[2:3]
	v_mov_b64_e32 v[78:79], v[2:3]
	v_mov_b64_e32 v[90:91], v[2:3]
	v_mov_b64_e32 v[94:95], v[2:3]
	v_mov_b64_e32 v[106:107], v[2:3]
	v_mov_b64_e32 v[110:111], v[2:3]
	v_mov_b64_e32 v[122:123], v[2:3]
	v_mov_b64_e32 v[126:127], v[2:3]
	s_mov_b32 s50, 0
	v_mov_b64_e32 v[140:141], 0x100
	v_mov_b64_e32 v[142:143], 0xff
	s_add_i32 s51, 0, 0x10000
	s_add_i32 s56, 0, 0x14000
	s_mov_b64 s[18:19], 0x10000
	v_mov_b64_e32 v[4:5], v[0:1]
	v_mov_b64_e32 v[16:17], v[0:1]
	v_mov_b64_e32 v[20:21], v[0:1]
	v_mov_b64_e32 v[32:33], v[0:1]
	v_mov_b64_e32 v[36:37], v[0:1]
	v_mov_b64_e32 v[48:49], v[0:1]
	v_mov_b64_e32 v[52:53], v[0:1]
	v_mov_b64_e32 v[8:9], v[0:1]
	v_mov_b64_e32 v[12:13], v[0:1]
	v_mov_b64_e32 v[24:25], v[0:1]
	v_mov_b64_e32 v[28:29], v[0:1]
	v_mov_b64_e32 v[40:41], v[0:1]
	v_mov_b64_e32 v[44:45], v[0:1]
	v_mov_b64_e32 v[56:57], v[0:1]
	v_mov_b64_e32 v[60:61], v[0:1]
	v_mov_b64_e32 v[64:65], v[0:1]
	v_mov_b64_e32 v[68:69], v[0:1]
	v_mov_b64_e32 v[80:81], v[0:1]
	v_mov_b64_e32 v[84:85], v[0:1]
	v_mov_b64_e32 v[96:97], v[0:1]
	v_mov_b64_e32 v[100:101], v[0:1]
	v_mov_b64_e32 v[112:113], v[0:1]
	v_mov_b64_e32 v[116:117], v[0:1]
	v_mov_b64_e32 v[72:73], v[0:1]
	v_mov_b64_e32 v[76:77], v[0:1]
	v_mov_b64_e32 v[88:89], v[0:1]
	v_mov_b64_e32 v[92:93], v[0:1]
	v_mov_b64_e32 v[104:105], v[0:1]
	v_mov_b64_e32 v[108:109], v[0:1]
	v_mov_b64_e32 v[120:121], v[0:1]
	v_mov_b64_e32 v[124:125], v[0:1]
	s_barrier
	s_branch .LBB0_608
